# attention: first key-half K fragment reads issued immediately after the tile barrier (address precomputed before the barrier), ahead of the loop bookkeeping and next-tile global loads
# speedup vs baseline: 1.0001x; 1.0001x over previous
; #define LAS __attribute__((address_space(3)))
; #define ATT_LOAD(t) do { kr0 = *(const u32x4*)(Kg + (size_t)(t) * 12288 + tid * 16); if (tid < 256) kr1 = *(const u32x4*)(Kg + (size_t)(t) * 12288 + (tid + 512) * 16); vr = *(const u32x4*)(Vg + (size_t)(t) * (64 * 3584)); } while (0)
; __device__ __forceinline__ void attn_unit(int bh, int qb, const bf16_t* QKV, const bf16_t* KF, const float* cstab, const float* qg, bf16_t* MIX, LAS unsigned char* lds) {
;     ...
;     for (int t = 0; t < NT; ++t) {
;         LAS unsigned char* buf = lds + (t & 1) * BUFB;
;         if (t + 1 < NT) ATT_LOAD(t + 1);
; #pragma unroll
;         for (int kb = 0; kb < 2; ++kb) {
;             const int key0 = 64 * t + 32 * kb;
;             if (key0 > qw + 31) continue;
;             const LAS unsigned char* kp = buf + (32 * kb + r32) * KROW + 16 * hi;
;             f32x16 p = negm;
;             bf16x8 kfr[6];
; #pragma unroll
;             for (int d0 = 0; d0 < 6; ++d0) kfr[d0] = *(const LAS bf16x8*)(kp + 32 * d0);
.LBB0_1054:
	s_waitcnt vmcnt(1)
	ds_write_b128 v141, v[70:73] offset:25600
	s_and_saveexec_b64 s[4:5], s[6:7]
	ds_write_b128 v140, v[66:69] offset:25600
	s_or_b64 exec, exec, s[4:5]
	s_lshl_b32 s41, s23, 2
	s_lshl_b32 s4, s27, 5
	s_add_i32 s41, s41, 4
	s_and_b32 s38, s4, 0x700
	s_add_u32 s4, s38, s35
	s_addc_u32 s5, 0, s34
	v_lshl_add_u64 v[48:49], s[4:5], 0, v[112:113]
	s_add_u32 s4, s24, s31
	v_lshl_add_u64 v[48:49], v[48:49], 0, v[64:65]
	s_addc_u32 s5, s25, s30
	s_mov_b32 s40, 2
	v_lshl_add_u64 v[112:113], s[12:13], 0, v[48:49]
	v_lshl_add_u64 v[108:109], s[4:5], 0, v[108:109]
	v_lshl_add_u64 v[110:111], s[4:5], 0, v[110:111]
	s_add_i32 s42, s22, 0xc0
	s_mov_b32 s43, 0
	s_waitcnt vmcnt(0)
	ds_write_b128 v142, v[86:89] offset:38912
	s_waitcnt lgkmcnt(0)
	s_barrier
	s_and_b32 s100, 1, s40
	s_cselect_b32 s100, 0, 0x6400
	v_add_u32_e32 v173, s100, v102
	v_add_u32_e32 v173, v173, v114
	ds_read_b128 v[122:125], v173
	ds_read_b128 v[126:129], v173 offset:32
	ds_read_b128 v[130:133], v173 offset:64
	ds_read_b128 v[140:143], v173 offset:96
	ds_read_b128 v[144:147], v173 offset:128
	ds_read_b128 v[148:151], v173 offset:160
	s_cmp_lt_u32 s40, s41
	s_cselect_b64 s[4:5], -1, 0
	s_cmp_ge_u32 s40, s41
	s_cbranch_scc1 .LBB0_1061
	s_branch .LBB0_1058
.LBB0_1057:
	ds_read_b128 v[122:125], v173
	ds_read_b128 v[126:129], v173 offset:32
	ds_read_b128 v[130:133], v173 offset:64
	ds_read_b128 v[140:143], v173 offset:96
	ds_read_b128 v[144:147], v173 offset:128
	ds_read_b128 v[148:151], v173 offset:160
	s_mov_b32 s43, s22
	s_cmp_lt_u32 s40, s41
	s_cselect_b64 s[4:5], -1, 0
	s_cmp_ge_u32 s40, s41
	s_cbranch_scc1 .LBB0_1061

; #define LAS __attribute__((address_space(3)))
; #define MFMA32(a, b, c) __builtin_amdgcn_mfma_f32_32x32x16_bf16(a, b, c, 0, 0, 0)
; __device__ __forceinline__ void attn_unit(int bh, int qb, const bf16_t* QKV, const bf16_t* KF, const float* cstab, const float* qg, bf16_t* MIX, LAS unsigned char* lds) {
;     ...
;             const int key0 = 64 * t + 32 * kb;
;             if (key0 > qw + 31) continue;
;             const LAS unsigned char* kp = buf + (32 * kb + r32) * KROW + 16 * hi;
;             f32x16 p = negm;
;             bf16x8 kfr[6];
; #pragma unroll
;             for (int d0 = 0; d0 < 6; ++d0) kfr[d0] = *(const LAS bf16x8*)(kp + 32 * d0);
;             __builtin_amdgcn_s_setprio(1);
; #pragma unroll
;             for (int d0 = 0; d0 < 6; ++d0) p = MFMA32(kfr[d0], qf[d0], p);
;             __builtin_amdgcn_s_setprio(0);
;             if (key0 + 31 > qw) {
; #pragma unroll
;                 for (int r = 0; r < 16; ++r) { const int key = key0 + (r & 3) + 8 * (r >> 2) + 4 * hi; if (key > q) p[r] = -1e30f; }
.LBB0_1061:
	s_and_b32 s23, 1, s40
	s_cselect_b32 s22, 0, 0x6400
	s_add_i32 s44, s22, 0
	s_add_i32 s22, s43, 64
	v_add_u32_e32 v48, s44, v102
	v_add_u32_e32 v119, s44, v118
	s_cmp_gt_i32 s22, s2
	v_add_u32_e32 v120, v48, v114
	s_cbranch_scc1 .LBB0_1068
	s_setprio 1
	s_waitcnt lgkmcnt(5)
	v_mfma_f32_32x32x16_bf16 v[48:63], v[122:125], v[74:77], v[32:47]
	s_waitcnt lgkmcnt(4)
	v_mfma_f32_32x32x16_bf16 v[48:63], v[126:129], v[78:81], v[48:63]
	s_waitcnt lgkmcnt(3)
	v_mfma_f32_32x32x16_bf16 v[48:63], v[130:133], v[82:85], v[48:63]
	s_waitcnt lgkmcnt(2)
	v_mfma_f32_32x32x16_bf16 v[48:63], v[140:143], v[90:93], v[48:63]
	s_waitcnt lgkmcnt(1)
	v_mfma_f32_32x32x16_bf16 v[48:63], v[144:147], v[94:97], v[48:63]
	s_waitcnt lgkmcnt(0)
	v_mfma_f32_32x32x16_bf16 v[48:63], v[148:151], v[98:101], v[48:63]
	v_add_u32_e32 v172, v119, v115
	ds_read_b64_tr_b16 v[156:157], v172 offset:13312
	ds_read_b64_tr_b16 v[158:159], v172 offset:14848
	ds_read_b64_tr_b16 v[160:161], v172 offset:16384
	ds_read_b64_tr_b16 v[162:163], v172 offset:17920
	ds_read_b64_tr_b16 v[164:165], v172 offset:13376
	ds_read_b64_tr_b16 v[166:167], v172 offset:14912
	ds_read_b64_tr_b16 v[168:169], v172 offset:16448
	ds_read_b64_tr_b16 v[170:171], v172 offset:17984
	ds_read_b128 v[202:205], v120 offset:6656
	ds_read_b128 v[206:209], v120 offset:6688
	ds_read_b128 v[210:213], v120 offset:6720
	ds_read_b128 v[214:217], v120 offset:6752
	ds_read_b128 v[218:221], v120 offset:6784
	ds_read_b128 v[222:225], v120 offset:6816
	s_setprio 0
	s_add_i32 s44, s43, 0x5f
	s_cmp_le_i32 s44, s37
	s_cbranch_scc1 .LBB0_1064
	v_add_u32_e32 v121, s43, v105
	v_add_u32_e32 v122, 64, v121
	v_cmp_lt_i32_e32 vcc, v122, v139
	s_nop 4
	v_cndmask_b32_e32 v49, v239, v49, vcc
	v_cmp_le_i32_e32 vcc, v122, v139
	v_add_u32_e32 v122, 0x42, v121
	s_nop 0
	v_cndmask_b32_e32 v48, v239, v48, vcc
	v_cmp_le_i32_e32 vcc, v122, v139
	v_add_u32_e32 v122, 0x43, v121
	s_nop 0
	v_cndmask_b32_e32 v50, v239, v50, vcc
	v_cmp_le_i32_e32 vcc, v122, v139
	v_add_u32_e32 v122, 0x48, v121
	s_nop 0
	v_cndmask_b32_e32 v51, v239, v51, vcc
	v_cmp_le_i32_e32 vcc, v122, v139
	v_add_u32_e32 v122, 0x49, v121
	s_nop 0
	v_cndmask_b32_e32 v52, v239, v52, vcc
	v_cmp_le_i32_e32 vcc, v122, v139
	v_add_u32_e32 v122, 0x4a, v121
	s_nop 0
	v_cndmask_b32_e32 v53, v239, v53, vcc
	v_cmp_le_i32_e32 vcc, v122, v139
	v_add_u32_e32 v122, 0x4b, v121
	s_nop 0
	v_cndmask_b32_e32 v54, v239, v54, vcc
	v_cmp_le_i32_e32 vcc, v122, v139
	v_add_u32_e32 v122, 0x50, v121
	s_nop 0
	v_cndmask_b32_e32 v55, v239, v55, vcc
	v_cmp_le_i32_e32 vcc, v122, v139
	v_add_u32_e32 v122, 0x51, v121
	s_nop 0
	v_cndmask_b32_e32 v56, v239, v56, vcc
	v_cmp_le_i32_e32 vcc, v122, v139
	v_add_u32_e32 v122, 0x52, v121
	s_nop 0
	v_cndmask_b32_e32 v57, v239, v57, vcc
	v_cmp_le_i32_e32 vcc, v122, v139
	v_add_u32_e32 v122, 0x53, v121
	s_nop 0
	v_cndmask_b32_e32 v58, v239, v58, vcc
	v_cmp_le_i32_e32 vcc, v122, v139
	v_add_u32_e32 v122, 0x58, v121
	s_nop 0
	v_cndmask_b32_e32 v59, v239, v59, vcc
	v_cmp_le_i32_e32 vcc, v122, v139
	v_add_u32_e32 v122, 0x59, v121
	s_nop 0
	v_cndmask_b32_e32 v60, v239, v60, vcc
	v_cmp_le_i32_e32 vcc, v122, v139
	v_add_u32_e32 v122, 0x5a, v121
	v_add_u32_e32 v121, 0x5b, v121
	v_cndmask_b32_e32 v61, v239, v61, vcc
	v_cmp_le_i32_e32 vcc, v122, v139
	s_nop 1
	v_cndmask_b32_e32 v62, v239, v62, vcc
	v_cmp_le_i32_e32 vcc, v121, v139
	s_nop 1
	v_cndmask_b32_e32 v63, v239, v63, vcc

; __device__ __forceinline__ unsigned cvt_pk_bf16(float lo, float hi) { const f32x2c_ v = {lo, hi}; const bf16x2c_ b = __builtin_convertvector(v, bf16x2c_); return __builtin_bit_cast(unsigned, b); }
; __device__ __forceinline__ float sum32(float v) { const auto rr = __builtin_amdgcn_permlane32_swap(__float_as_uint(v), __float_as_uint(v), false, false); return __uint_as_float(rr[0]) + __uint_as_float(rr[1]); }
; #define LAS __attribute__((address_space(3)))
; __device__ __forceinline__ void attn_unit(int bh, int qb, const bf16_t* QKV, const bf16_t* KF, const float* cstab, const float* qg, bf16_t* MIX, LAS unsigned char* lds) {
;     ...
;     const int b = bh >> 3, h = bh & 7, q0 = qb * 256, qw = q0 + 32 * wid, q = qw + r32;
;     bf16x8 qf[6];
;     {
;         const bf16_t* Qp = QKV + (size_t)(b * SEQ + q) * 1792 + h * 96 + 8 * hi;
;         const float* cs = cstab + (size_t)(b * SEQ + q) * 32 + 8 * hi;
;         u32x4 raw[6];
; #pragma unroll
;         for (int d0 = 0; d0 < 6; ++d0) raw[d0] = *(const u32x4*)(Qp + 16 * d0);
;     ...
;         __syncthreads();
;     }
;     const float l = pg8::sum32(lrun), inv = 1.0f / l;
;     {
;         constexpr int OROW = 144;
;         LAS unsigned char* stg = lds + 2 * BUFB + wid * (32 * OROW);
; #pragma unroll
;         for (int rg = 0; rg < 4; ++rg) {
;             u32x2 w; w.x = cvt_pk_bf16(o0[4 * rg] * inv, o0[4 * rg + 1] * inv); w.y = cvt_pk_bf16(o0[4 * rg + 2] * inv, o0[4 * rg + 3] * inv);
;             u32x2 x; x.x = cvt_pk_bf16(o1[4 * rg] * inv, o1[4 * rg + 1] * inv); x.y = cvt_pk_bf16(o1[4 * rg + 2] * inv, o1[4 * rg + 3] * inv);
;             *(LAS u32x2*)(stg + r32 * OROW + (8 * rg + 4 * hi) * 2) = w; *(LAS u32x2*)(stg + r32 * OROW + (32 + 8 * rg + 4 * hi) * 2) = x;
;         }
;         asm volatile("s_waitcnt lgkmcnt(0)" ::: "memory");
;         bf16_t* dst = MIX + ((size_t)(b * SEQ + qw)) * 1024 + h * 64 + (lane & 7) * 8;
; #pragma unroll
;         for (int it = 0; it < 4; ++it) { const int row = it * 8 + (lane >> 3); const u32x4 v = *(const LAS u32x4*)(stg + row * OROW + (lane & 7) * 16); *(u32x4*)(dst + (size_t)row * 1024) = v; }
.LBB0_1077:
	s_add_i32 s40, s40, 1
	s_and_b32 s100, 1, s40
	s_cselect_b32 s100, 0, 0x6400
	v_add_u32_e32 v173, s100, v102
	v_add_u32_e32 v173, v173, v114
	v_lshl_add_u64 v[112:113], v[112:113], 0, s[82:83]
	v_lshl_add_u64 v[108:109], v[108:109], 0, s[96:97]
	s_cmp_lg_u32 s42, s22
	v_lshl_add_u64 v[110:111], v[110:111], 0, s[96:97]
	s_waitcnt lgkmcnt(0)
	s_barrier
	s_cbranch_scc1 .LBB0_1057
	v_mov_b32_e32 v32, v107
	s_nop 1
	v_permlane32_swap_b32_e32 v107, v32
	v_add_f32_e32 v32, v107, v32
	v_div_scale_f32 v33, s[4:5], v32, v32, 1.0
	v_rcp_f32_e32 v34, v33
	s_mulk_i32 s39, 0x1200
	s_add_i32 s2, s39, 0
	s_add_i32 s4, s37, s28
	v_fma_f32 v35, -v33, v34, 1.0
	v_fmac_f32_e32 v34, v35, v34
	v_div_scale_f32 v35, vcc, 1.0, v32, 1.0
	v_mul_f32_e32 v36, v35, v34
	v_fma_f32 v37, -v33, v36, v35
	v_fmac_f32_e32 v36, v37, v34
	v_fma_f32 v33, -v33, v36, v35
	v_div_fmas_f32 v33, v33, v34, v36
	v_div_fixup_f32 v32, v33, v32, 1.0
	v_mul_u32_u24_e32 v33, 0x90, v138
	v_add3_u32 v33, s2, v33, v117
	v_pk_mul_f32 v[0:1], v[0:1], v[32:33] op_sel_hi:[1,0]
	v_pk_mul_f32 v[2:3], v[2:3], v[32:33] op_sel_hi:[1,0]
	v_cvt_pk_bf16_f32 v0, v0, v1
	v_cvt_pk_bf16_f32 v1, v2, v3
	v_pk_mul_f32 v[2:3], v[16:17], v[32:33] op_sel_hi:[1,0]
	v_pk_mul_f32 v[16:17], v[18:19], v[32:33] op_sel_hi:[1,0]
	v_pk_mul_f32 v[4:5], v[4:5], v[32:33] op_sel_hi:[1,0]
	v_pk_mul_f32 v[6:7], v[6:7], v[32:33] op_sel_hi:[1,0]
	v_cvt_pk_bf16_f32 v2, v2, v3
	v_cvt_pk_bf16_f32 v3, v16, v17
	v_cvt_pk_bf16_f32 v4, v4, v5
	v_cvt_pk_bf16_f32 v5, v6, v7
	v_pk_mul_f32 v[6:7], v[20:21], v[32:33] op_sel_hi:[1,0]
	v_pk_mul_f32 v[16:17], v[22:23], v[32:33] op_sel_hi:[1,0]
	v_cvt_pk_bf16_f32 v6, v6, v7
	v_cvt_pk_bf16_f32 v7, v16, v17
	v_add_u32_e32 v16, 0xc800, v33
	ds_write2_b64 v16, v[0:1], v[4:5] offset1:2
	ds_write2_b64 v16, v[2:3], v[6:7] offset0:8 offset1:10
	v_pk_mul_f32 v[0:1], v[8:9], v[32:33] op_sel_hi:[1,0]
	v_pk_mul_f32 v[2:3], v[10:11], v[32:33] op_sel_hi:[1,0]
	v_cvt_pk_bf16_f32 v0, v0, v1
	v_cvt_pk_bf16_f32 v1, v2, v3
	v_pk_mul_f32 v[2:3], v[24:25], v[32:33] op_sel_hi:[1,0]
	v_pk_mul_f32 v[4:5], v[26:27], v[32:33] op_sel_hi:[1,0]
	v_cvt_pk_bf16_f32 v2, v2, v3
	v_cvt_pk_bf16_f32 v3, v4, v5
	v_pk_mul_f32 v[4:5], v[12:13], v[32:33] op_sel_hi:[1,0]
	v_pk_mul_f32 v[6:7], v[14:15], v[32:33] op_sel_hi:[1,0]
	v_cvt_pk_bf16_f32 v4, v4, v5
	v_cvt_pk_bf16_f32 v5, v6, v7
	v_pk_mul_f32 v[6:7], v[28:29], v[32:33] op_sel_hi:[1,0]
	v_pk_mul_f32 v[8:9], v[30:31], v[32:33] op_sel_hi:[1,0]
	s_ashr_i32 s5, s4, 31
	v_cvt_pk_bf16_f32 v6, v6, v7
	v_cvt_pk_bf16_f32 v7, v8, v9
	ds_write2_b64 v16, v[0:1], v[4:5] offset0:4 offset1:6
	ds_write2_b64 v16, v[2:3], v[6:7] offset0:12 offset1:14
	s_lshl_b64 s[4:5], s[4:5], 11
	v_lshrrev_b32_e32 v4, 3, v116
	s_add_u32 s4, s16, s4
	v_mul_u32_u24_e32 v0, 0x90, v4
	s_waitcnt lgkmcnt(0)
	s_addc_u32 s5, s17, s5
	s_lshl_b32 s6, s36, 7
	v_add3_u32 v12, s2, v64, v0
	s_add_u32 s4, s4, s6
	ds_read_b128 v[0:3], v12 offset:51200
	s_addc_u32 s5, s5, 0
	v_lshl_add_u64 v[8:9], s[4:5], 0, v[64:65]
	v_lshlrev_b32_e32 v64, 11, v4
	ds_read_b128 v[4:7], v12 offset:52352
	v_lshl_add_u64 v[10:11], v[8:9], 0, v[64:65]
	s_waitcnt lgkmcnt(1)
	global_store_dwordx4 v[10:11], v[0:3], off
	v_or_b32_e32 v10, 0x8000, v64
	v_mov_b32_e32 v11, v65
	v_or_b32_e32 v0, 0x4000, v64
	v_mov_b32_e32 v1, v65
	v_lshl_add_u64 v[0:1], v[8:9], 0, v[0:1]
	s_waitcnt lgkmcnt(0)
	global_store_dwordx4 v[0:1], v[4:7], off
	ds_read_b128 v[0:3], v12 offset:53504
	ds_read_b128 v[4:7], v12 offset:54656
	v_lshl_add_u64 v[10:11], v[8:9], 0, v[10:11]
	v_or_b32_e32 v64, 0xc000, v64
	v_mov_b32_e32 v143, v228
	s_waitcnt lgkmcnt(1)
	global_store_dwordx4 v[10:11], v[0:3], off
	v_mov_b32_e32 v103, v65
	s_nop 0
	v_lshl_add_u64 v[0:1], v[8:9], 0, v[64:65]
	s_waitcnt lgkmcnt(0)
	global_store_dwordx4 v[0:1], v[4:7], off
	v_mov_b64_e32 v[2:3], s[80:81]
	v_readfirstlane_b32 s2, v143
	s_ashr_i32 s23, s2, 6
	s_lshl_b32 s2, s29, 8
	s_lshl_b32 s22, s23, 5
	v_and_b32_e32 v138, 31, v143
	s_add_i32 s22, s22, s2
	v_or_b32_e32 v139, s22, v138
	v_add_u32_e32 v0, s28, v139
	v_bfe_u32 v144, v143, 5, 1
	v_mad_i64_i32 v[2:3], s[4:5], v0, s85, v[2:3]
	v_lshl_add_u64 v[2:3], v[2:3], 0, s[78:79]
	v_lshlrev_b32_e32 v102, 4, v144
	v_lshl_add_u64 v[2:3], v[2:3], 0, v[102:103]
	global_load_dwordx4 v[32:35], v[2:3], off offset:128
	global_load_dwordx4 v[36:39], v[2:3], off offset:160
	global_load_dwordx4 v[40:43], v[2:3], off offset:96
	global_load_dwordx4 v[48:51], v[2:3], off offset:64
	global_load_dwordx4 v[56:59], v[2:3], off offset:32
	global_load_dwordx4 v[66:69], v[2:3], off
	v_ashrrev_i32_e32 v1, 31, v0
	v_lshlrev_b64 v[0:1], 7, v[0:1]
	v_lshl_add_u64 v[0:1], s[8:9], 0, v[0:1]
	v_and_b32_e32 v64, 32, v143
	v_lshl_add_u64 v[28:29], v[0:1], 0, v[64:65]
	global_load_dwordx4 v[4:7], v64, s[0:1] offset:272
	global_load_dwordx4 v[24:27], v64, s[0:1] offset:256
	global_load_dwordx4 v[8:11], v64, s[0:1] offset:336
	global_load_dwordx4 v[20:23], v64, s[0:1] offset:320
	global_load_dwordx4 v[0:3], v[28:29], off offset:16
	global_load_dwordx4 v[16:19], v[28:29], off
	global_load_dwordx4 v[12:15], v[28:29], off offset:80
	s_nop 0
	global_load_dwordx4 v[28:31], v[28:29], off offset:64
	v_lshlrev_b32_e32 v108, 4, v143
	v_ashrrev_i32_e32 v109, 31, v108
	v_add_u32_e32 v74, 0x200, v143
	s_movk_i32 s2, 0x100
	v_lshlrev_b32_e32 v110, 4, v74
	v_cmp_gt_i32_e64 s[6:7], s2, v143
	v_ashrrev_i32_e32 v111, 31, v110
	s_waitcnt vmcnt(13)
	v_lshlrev_b32_e32 v94, 16, v35
	v_and_b32_e32 v95, 0xffff0000, v35
	s_waitcnt vmcnt(12)
	v_lshlrev_b32_e32 v96, 16, v39
	v_and_b32_e32 v97, 0xffff0000, v39
	v_lshlrev_b32_e32 v98, 16, v34
	s_waitcnt vmcnt(8)
; __device__ __forceinline__ float sum32(float v) { const auto rr = __builtin_amdgcn_permlane32_swap(__float_as_uint(v), __float_as_uint(v), false, false); return __uint_as_float(rr[0]) + __uint_as_float(rr[1]); }
; __device__ __forceinline__ u32x4 pack8(const float* v) { u32x4 w; w.x = cvt_pk_bf16(v[0], v[1]); w.y = cvt_pk_bf16(v[2], v[3]); w.z = cvt_pk_bf16(v[4], v[5]); w.w = cvt_pk_bf16(v[6], v[7]); return w; }
; __device__ __forceinline__ void attn_unit(int bh, int qb, const bf16_t* QKV, const bf16_t* KF, const float* cstab, const float* qg, bf16_t* MIX, LAS unsigned char* lds) {
;     ...
;         for (int d0 = 0; d0 < 6; ++d0) raw[d0] = *(const u32x4*)(Qp + 16 * d0);
;         float ss = 0.f;
; #pragma unroll
;         for (int d0 = 0; d0 < 6; ++d0) { float v[8]; unpack8(raw[d0], v);
; #pragma unroll
;             for (int i = 0; i < 8; ++i) ss += v[i] * v[i]; }
;         ss = pg8::sum32(ss);
;         const float rs = __builtin_amdgcn_rsqf(ss * (1.0f / 96.0f) + EPS) * C2Q;
; #pragma unroll
;         for (int d0 = 0; d0 < 4; ++d0) { float v[8]; unpack8(raw[d0], v);
; #pragma unroll
;             for (int i = 0; i < 8; ++i) v[i] = v[i] * rs * qg[16 * d0 + 8 * hi + i];
;             qf[d0] = __builtin_bit_cast(bf16x8, pack8(v)); }
;         float x1[8], x2[8], o1[8], o2[8]; unpack8(raw[4], x1); unpack8(raw[5], x2);
; #pragma unroll
;         for (int i = 0; i < 8; ++i) { const float y1 = x1[i] * rs * qg[64 + 8 * hi + i], y2 = x2[i] * rs * qg[80 + 8 * hi + i], co = cs[i], si = cs[16 + i];
;             o1[i] = y1 * co - y2 * si; o2[i] = y1 * si + y2 * co; }
;         qf[4] = __builtin_bit_cast(bf16x8, pack8(o1)); qf[5] = __builtin_bit_cast(bf16x8, pack8(o2));
;     }
;     const char* Kg = (const char*)(KF + (size_t)bh * SEQ * 96);
;     const char* Vg = (const char*)(QKV + (size_t)b * SEQ * 1792 + 768 + h * 128 + 64) + (size_t)(tid >> 3) * 3584 + (tid & 7) * 16;
;     const int kofs0 = (tid / 12) * KROW + (tid % 12) * 16, kofs1 = ((tid + 512) / 12) * KROW + ((tid + 512) % 12) * 16, vofs = KBUF + (tid >> 3) * VROW + (tid & 7) * 16;
;     const int vtb = KBUF + (4 * hi + ((lane & 15) >> 2)) * VROW + (16 * ((lane >> 4) & 1) + 4 * (lane & 3)) * 2;
;     const int NT = 4 * (qb + 1);
;     u32x4 kr0, kr1 = {0u, 0u, 0u, 0u}, vr;
	v_lshlrev_b32_e32 v126, 16, v69
	v_and_b32_e32 v127, 0xffff0000, v69
	v_lshlrev_b32_e32 v128, 16, v68
	v_and_b32_e32 v129, 0xffff0000, v68
	v_lshl_add_u64 v[68:69], s[14:15], 0, v[108:109]
	v_and_b32_e32 v99, 0xffff0000, v34
	v_lshlrev_b32_e32 v100, 16, v38
	v_and_b32_e32 v101, 0xffff0000, v38
	v_lshlrev_b32_e32 v106, 16, v33
	v_and_b32_e32 v107, 0xffff0000, v33
	v_lshlrev_b32_e32 v112, 16, v37
	v_and_b32_e32 v113, 0xffff0000, v37
	v_lshlrev_b32_e32 v114, 16, v32
	v_and_b32_e32 v115, 0xffff0000, v32
	v_lshlrev_b32_e32 v116, 16, v36
	v_and_b32_e32 v117, 0xffff0000, v36
	v_lshlrev_b32_e32 v90, 16, v43
	v_and_b32_e32 v91, 0xffff0000, v43
	global_load_dwordx4 v[32:35], v64, s[0:1] offset:208
	global_load_dwordx4 v[36:39], v64, s[0:1] offset:192
	v_lshlrev_b32_e32 v92, 16, v42
	v_and_b32_e32 v93, 0xffff0000, v42
	v_lshlrev_b32_e32 v118, 16, v41
	v_and_b32_e32 v119, 0xffff0000, v41
	v_lshlrev_b32_e32 v120, 16, v40
	v_and_b32_e32 v121, 0xffff0000, v40
	v_lshlrev_b32_e32 v82, 16, v51
	v_and_b32_e32 v83, 0xffff0000, v51
	global_load_dwordx4 v[40:43], v64, s[0:1] offset:144
	global_load_dwordx4 v[44:47], v64, s[0:1] offset:128
	v_lshlrev_b32_e32 v84, 16, v50
	v_and_b32_e32 v85, 0xffff0000, v50
	v_lshlrev_b32_e32 v122, 16, v49
	v_and_b32_e32 v123, 0xffff0000, v49
	v_lshlrev_b32_e32 v124, 16, v48
	v_and_b32_e32 v125, 0xffff0000, v48
	v_lshlrev_b32_e32 v78, 16, v59
	v_and_b32_e32 v79, 0xffff0000, v59
	global_load_dwordx4 v[48:51], v64, s[0:1] offset:80
	global_load_dwordx4 v[52:55], v64, s[0:1] offset:64
	v_lshlrev_b32_e32 v80, 16, v58
	v_and_b32_e32 v81, 0xffff0000, v58
	v_lshlrev_b32_e32 v86, 16, v57
	v_and_b32_e32 v87, 0xffff0000, v57
	v_lshlrev_b32_e32 v88, 16, v56
	v_and_b32_e32 v89, 0xffff0000, v56
	global_load_dwordx4 v[56:59], v64, s[0:1] offset:16
	global_load_dwordx4 v[60:63], v64, s[0:1]
	global_load_dwordx4 v[70:73], v[68:69], off
	v_and_b32_e32 v133, 0xffff0000, v66
	v_lshlrev_b32_e32 v132, 16, v66
	v_mul_f32_e32 v64, v133, v133
	v_lshlrev_b32_e32 v130, 16, v67
	v_and_b32_e32 v131, 0xffff0000, v67
	v_pk_fma_f32 v[66:67], v[132:133], v[132:133], v[64:65] op_sel_hi:[1,1,0]
	v_mul_f32_e32 v64, v131, v131
	v_pk_fma_f32 v[66:67], v[130:131], v[130:131], v[66:67]
	s_nop 0
	v_pk_add_f32 v[66:67], v[64:65], v[66:67] op_sel_hi:[0,1]
	v_pk_fma_f32 v[66:67], v[128:129], v[128:129], v[66:67]
	v_mul_f32_e32 v64, v129, v129
	v_pk_add_f32 v[66:67], v[64:65], v[66:67] op_sel_hi:[0,1]
	v_pk_fma_f32 v[66:67], v[126:127], v[126:127], v[66:67]
	v_mul_f32_e32 v64, v127, v127
	v_pk_add_f32 v[66:67], v[64:65], v[66:67] op_sel_hi:[0,1]
	v_pk_fma_f32 v[66:67], v[88:89], v[88:89], v[66:67]
	v_mul_f32_e32 v64, v89, v89
	v_pk_add_f32 v[66:67], v[64:65], v[66:67] op_sel_hi:[0,1]
	v_pk_fma_f32 v[66:67], v[86:87], v[86:87], v[66:67]
	v_mul_f32_e32 v64, v87, v87
	v_pk_add_f32 v[66:67], v[64:65], v[66:67] op_sel_hi:[0,1]
	v_pk_fma_f32 v[66:67], v[80:81], v[80:81], v[66:67]
	v_mul_f32_e32 v64, v81, v81
	v_pk_add_f32 v[66:67], v[64:65], v[66:67] op_sel_hi:[0,1]
	v_pk_fma_f32 v[66:67], v[78:79], v[78:79], v[66:67]
	v_mul_f32_e32 v64, v79, v79
	v_pk_add_f32 v[66:67], v[64:65], v[66:67] op_sel_hi:[0,1]
	v_pk_fma_f32 v[66:67], v[124:125], v[124:125], v[66:67]
	v_mul_f32_e32 v64, v125, v125
	v_pk_add_f32 v[66:67], v[64:65], v[66:67] op_sel_hi:[0,1]
	v_pk_fma_f32 v[66:67], v[122:123], v[122:123], v[66:67]
	v_mul_f32_e32 v64, v123, v123
	v_pk_add_f32 v[66:67], v[64:65], v[66:67] op_sel_hi:[0,1]
	v_pk_fma_f32 v[66:67], v[84:85], v[84:85], v[66:67]
	v_mul_f32_e32 v64, v85, v85
	v_pk_add_f32 v[66:67], v[64:65], v[66:67] op_sel_hi:[0,1]
	v_pk_fma_f32 v[66:67], v[82:83], v[82:83], v[66:67]
	v_mul_f32_e32 v64, v83, v83
	v_pk_add_f32 v[66:67], v[64:65], v[66:67] op_sel_hi:[0,1]
	v_pk_fma_f32 v[66:67], v[120:121], v[120:121], v[66:67]
	v_mul_f32_e32 v64, v121, v121
	v_pk_add_f32 v[66:67], v[64:65], v[66:67] op_sel_hi:[0,1]
	v_pk_fma_f32 v[66:67], v[118:119], v[118:119], v[66:67]
	v_mul_f32_e32 v64, v119, v119
	v_pk_add_f32 v[66:67], v[64:65], v[66:67] op_sel_hi:[0,1]
	v_pk_fma_f32 v[66:67], v[92:93], v[92:93], v[66:67]
	v_mul_f32_e32 v64, v93, v93
	v_pk_add_f32 v[66:67], v[64:65], v[66:67] op_sel_hi:[0,1]
	v_pk_fma_f32 v[66:67], v[90:91], v[90:91], v[66:67]
	v_mul_f32_e32 v64, v91, v91
	v_pk_add_f32 v[66:67], v[64:65], v[66:67] op_sel_hi:[0,1]
	v_pk_fma_f32 v[66:67], v[114:115], v[114:115], v[66:67]
	v_mul_f32_e32 v64, v115, v115
	v_pk_add_f32 v[66:67], v[64:65], v[66:67] op_sel_hi:[0,1]
	v_pk_fma_f32 v[66:67], v[106:107], v[106:107], v[66:67]
	v_mul_f32_e32 v64, v107, v107
	v_pk_add_f32 v[66:67], v[64:65], v[66:67] op_sel_hi:[0,1]
	v_pk_fma_f32 v[66:67], v[98:99], v[98:99], v[66:67]
	v_mul_f32_e32 v64, v99, v99
	v_pk_add_f32 v[66:67], v[64:65], v[66:67] op_sel_hi:[0,1]
	v_pk_fma_f32 v[66:67], v[94:95], v[94:95], v[66:67]
	v_mul_f32_e32 v64, v95, v95
	v_pk_add_f32 v[66:67], v[64:65], v[66:67] op_sel_hi:[0,1]
	v_pk_fma_f32 v[66:67], v[116:117], v[116:117], v[66:67]
	v_mul_f32_e32 v64, v117, v117
	v_pk_add_f32 v[66:67], v[64:65], v[66:67] op_sel_hi:[0,1]
	v_pk_fma_f32 v[66:67], v[112:113], v[112:113], v[66:67]
	v_mul_f32_e32 v64, v113, v113
	v_pk_add_f32 v[66:67], v[64:65], v[66:67] op_sel_hi:[0,1]
	v_pk_fma_f32 v[66:67], v[100:101], v[100:101], v[66:67]
	v_mul_f32_e32 v64, v101, v101
	v_pk_add_f32 v[66:67], v[64:65], v[66:67] op_sel_hi:[0,1]
	v_pk_fma_f32 v[66:67], v[96:97], v[96:97], v[66:67]
	v_mul_f32_e32 v64, v97, v97
	v_pk_add_f32 v[134:135], v[64:65], v[66:67] op_sel_hi:[0,1]
	v_mov_b32_e32 v66, v65
	v_mov_b32_e32 v67, v65
	v_mov_b32_e32 v146, v134
	v_mov_b32_e32 v64, v65
	v_mov_b64_e32 v[68:69], v[66:67]
	v_permlane32_swap_b32_e32 v134, v146
	v_mov_b64_e32 v[66:67], v[64:65]
	s_and_saveexec_b64 s[4:5], s[6:7]
	s_cbranch_execz .LBB0_1080
	v_lshl_add_u64 v[66:67], s[14:15], 0, v[110:111]
	global_load_dwordx4 v[66:69], v[66:67], off

; #define LAS __attribute__((address_space(3)))
; #define ATT_LOAD(t) do { kr0 = *(const u32x4*)(Kg + (size_t)(t) * 12288 + tid * 16); if (tid < 256) kr1 = *(const u32x4*)(Kg + (size_t)(t) * 12288 + (tid + 512) * 16); vr = *(const u32x4*)(Vg + (size_t)(t) * (64 * 3584)); } while (0)
; __device__ __forceinline__ void attn_unit(int bh, int qb, const bf16_t* QKV, const bf16_t* KF, const float* cstab, const float* qg, bf16_t* MIX, LAS unsigned char* lds) {
;     ...
;     for (int t = 0; t < NT; ++t) {
;         LAS unsigned char* buf = lds + (t & 1) * BUFB;
;         if (t + 1 < NT) ATT_LOAD(t + 1);
; #pragma unroll
;         for (int kb = 0; kb < 2; ++kb) {
;             const int key0 = 64 * t + 32 * kb;
;             if (key0 > qw + 31) continue;
;             const LAS unsigned char* kp = buf + (32 * kb + r32) * KROW + 16 * hi;
;             f32x16 p = negm;
;             bf16x8 kfr[6];
; #pragma unroll
;             for (int d0 = 0; d0 < 6; ++d0) kfr[d0] = *(const LAS bf16x8*)(kp + 32 * d0);
.LBB0_1095:
	s_waitcnt vmcnt(1)
	ds_write_b128 v142, v[70:73] offset:25600
	s_and_saveexec_b64 s[4:5], s[6:7]
	ds_write_b128 v140, v[66:69] offset:25600
	s_or_b64 exec, exec, s[4:5]
	s_and_b32 s4, s26, 7
	s_lshl_b32 s20, s29, 2
	s_lshl_b32 s4, s4, 8
	s_add_i32 s20, s20, 4
	s_or_b32 s21, s4, 0xc0
	s_add_u32 s4, s38, s35
	s_addc_u32 s5, 0, s34
	v_lshl_add_u64 v[48:49], s[4:5], 0, v[112:113]
	s_add_u32 s4, s24, s31
	v_lshl_add_u64 v[48:49], v[48:49], 0, v[64:65]
	s_addc_u32 s5, s25, s30
	s_mov_b32 s19, 2
	v_lshl_add_u64 v[112:113], s[12:13], 0, v[48:49]
	v_lshl_add_u64 v[108:109], s[4:5], 0, v[108:109]
	v_lshl_add_u64 v[110:111], s[4:5], 0, v[110:111]
	s_mov_b32 s29, 0
	s_waitcnt vmcnt(0)
	ds_write_b128 v141, v[86:89] offset:38912
	s_waitcnt lgkmcnt(0)
	s_barrier
	s_and_b32 s100, 1, s19
	s_cselect_b32 s100, 0, 0x6400
	v_add_u32_e32 v173, s100, v102
	v_add_u32_e32 v173, v173, v114
	ds_read_b128 v[122:125], v173
	ds_read_b128 v[126:129], v173 offset:32
	ds_read_b128 v[130:133], v173 offset:64
	ds_read_b128 v[140:143], v173 offset:96
	ds_read_b128 v[144:147], v173 offset:128
	ds_read_b128 v[148:151], v173 offset:160
	s_cmp_lt_u32 s19, s20
	s_cselect_b64 s[4:5], -1, 0
	s_cmp_ge_u32 s19, s20
	s_cbranch_scc1 .LBB0_1102
	s_branch .LBB0_1099
.LBB0_1098:
	ds_read_b128 v[122:125], v173
	ds_read_b128 v[126:129], v173 offset:32
	ds_read_b128 v[130:133], v173 offset:64
	ds_read_b128 v[140:143], v173 offset:96
	ds_read_b128 v[144:147], v173 offset:128
	ds_read_b128 v[148:151], v173 offset:160
	s_mov_b32 s29, s14
	s_cmp_lt_u32 s19, s20
	s_cselect_b64 s[4:5], -1, 0
	s_cmp_ge_u32 s19, s20
	s_cbranch_scc1 .LBB0_1102

; #define LAS __attribute__((address_space(3)))
; #define MFMA32(a, b, c) __builtin_amdgcn_mfma_f32_32x32x16_bf16(a, b, c, 0, 0, 0)
; __device__ __forceinline__ void attn_unit(int bh, int qb, const bf16_t* QKV, const bf16_t* KF, const float* cstab, const float* qg, bf16_t* MIX, LAS unsigned char* lds) {
;     ...
;             const int key0 = 64 * t + 32 * kb;
;             if (key0 > qw + 31) continue;
;             const LAS unsigned char* kp = buf + (32 * kb + r32) * KROW + 16 * hi;
;             f32x16 p = negm;
;             bf16x8 kfr[6];
; #pragma unroll
;             for (int d0 = 0; d0 < 6; ++d0) kfr[d0] = *(const LAS bf16x8*)(kp + 32 * d0);
;             __builtin_amdgcn_s_setprio(1);
; #pragma unroll
;             for (int d0 = 0; d0 < 6; ++d0) p = MFMA32(kfr[d0], qf[d0], p);
;             __builtin_amdgcn_s_setprio(0);
;             if (key0 + 31 > qw) {
; #pragma unroll
;                 for (int r = 0; r < 16; ++r) { const int key = key0 + (r & 3) + 8 * (r >> 2) + 4 * hi; if (key > q) p[r] = -1e30f; }
.LBB0_1102:
	s_and_b32 s15, 1, s19
	s_cselect_b32 s14, 0, 0x6400
	s_add_i32 s30, s14, 0
	s_add_i32 s14, s29, 64
	v_add_u32_e32 v48, s30, v102
	v_add_u32_e32 v119, s30, v118
	s_cmp_gt_i32 s14, s18
	v_add_u32_e32 v120, v48, v114
	s_cbranch_scc1 .LBB0_1109
	s_setprio 1
	s_waitcnt lgkmcnt(5)
	v_mfma_f32_32x32x16_bf16 v[48:63], v[122:125], v[74:77], v[32:47]
	s_waitcnt lgkmcnt(4)
	v_mfma_f32_32x32x16_bf16 v[48:63], v[126:129], v[78:81], v[48:63]
	s_waitcnt lgkmcnt(3)
	v_mfma_f32_32x32x16_bf16 v[48:63], v[130:133], v[82:85], v[48:63]
	s_waitcnt lgkmcnt(2)
	v_mfma_f32_32x32x16_bf16 v[48:63], v[140:143], v[90:93], v[48:63]
	s_waitcnt lgkmcnt(1)
	v_mfma_f32_32x32x16_bf16 v[48:63], v[144:147], v[94:97], v[48:63]
	s_waitcnt lgkmcnt(0)
	v_mfma_f32_32x32x16_bf16 v[48:63], v[148:151], v[98:101], v[48:63]
	v_add_u32_e32 v172, v119, v115
	ds_read_b64_tr_b16 v[156:157], v172 offset:13312
	ds_read_b64_tr_b16 v[158:159], v172 offset:14848
	ds_read_b64_tr_b16 v[160:161], v172 offset:16384
	ds_read_b64_tr_b16 v[162:163], v172 offset:17920
	ds_read_b64_tr_b16 v[164:165], v172 offset:13376
	ds_read_b64_tr_b16 v[166:167], v172 offset:14912
	ds_read_b64_tr_b16 v[168:169], v172 offset:16448
	ds_read_b64_tr_b16 v[170:171], v172 offset:17984
	ds_read_b128 v[202:205], v120 offset:6656
	ds_read_b128 v[206:209], v120 offset:6688
	ds_read_b128 v[210:213], v120 offset:6720
	ds_read_b128 v[214:217], v120 offset:6752
	ds_read_b128 v[218:221], v120 offset:6784
	ds_read_b128 v[222:225], v120 offset:6816
	s_setprio 0
	s_add_i32 s30, s29, 0x5f
	s_cmp_le_i32 s30, s22
	s_cbranch_scc1 .LBB0_1105
	v_add_u32_e32 v121, s29, v105
	v_add_u32_e32 v122, 64, v121
	v_cmp_lt_i32_e32 vcc, v122, v139
	s_nop 4
	v_cndmask_b32_e32 v49, v239, v49, vcc
	v_cmp_le_i32_e32 vcc, v122, v139
	v_add_u32_e32 v122, 0x42, v121
	s_nop 0
	v_cndmask_b32_e32 v48, v239, v48, vcc
	v_cmp_le_i32_e32 vcc, v122, v139
	v_add_u32_e32 v122, 0x43, v121
	s_nop 0
	v_cndmask_b32_e32 v50, v239, v50, vcc
	v_cmp_le_i32_e32 vcc, v122, v139
	v_add_u32_e32 v122, 0x48, v121
	s_nop 0
	v_cndmask_b32_e32 v51, v239, v51, vcc
	v_cmp_le_i32_e32 vcc, v122, v139
	v_add_u32_e32 v122, 0x49, v121
	s_nop 0
	v_cndmask_b32_e32 v52, v239, v52, vcc
	v_cmp_le_i32_e32 vcc, v122, v139
	v_add_u32_e32 v122, 0x4a, v121
	s_nop 0
	v_cndmask_b32_e32 v53, v239, v53, vcc
	v_cmp_le_i32_e32 vcc, v122, v139
	v_add_u32_e32 v122, 0x4b, v121
	s_nop 0
	v_cndmask_b32_e32 v54, v239, v54, vcc
	v_cmp_le_i32_e32 vcc, v122, v139
	v_add_u32_e32 v122, 0x50, v121
	s_nop 0
	v_cndmask_b32_e32 v55, v239, v55, vcc
	v_cmp_le_i32_e32 vcc, v122, v139
	v_add_u32_e32 v122, 0x51, v121
	s_nop 0
	v_cndmask_b32_e32 v56, v239, v56, vcc
	v_cmp_le_i32_e32 vcc, v122, v139
	v_add_u32_e32 v122, 0x52, v121
	s_nop 0
	v_cndmask_b32_e32 v57, v239, v57, vcc
	v_cmp_le_i32_e32 vcc, v122, v139
	v_add_u32_e32 v122, 0x53, v121
	s_nop 0
	v_cndmask_b32_e32 v58, v239, v58, vcc
	v_cmp_le_i32_e32 vcc, v122, v139
	v_add_u32_e32 v122, 0x58, v121
	s_nop 0
	v_cndmask_b32_e32 v59, v239, v59, vcc
	v_cmp_le_i32_e32 vcc, v122, v139
	v_add_u32_e32 v122, 0x59, v121
	s_nop 0
	v_cndmask_b32_e32 v60, v239, v60, vcc
	v_cmp_le_i32_e32 vcc, v122, v139
	v_add_u32_e32 v122, 0x5a, v121
	v_add_u32_e32 v121, 0x5b, v121
	v_cndmask_b32_e32 v61, v239, v61, vcc
	v_cmp_le_i32_e32 vcc, v122, v139
	s_nop 1
	v_cndmask_b32_e32 v62, v239, v62, vcc
	v_cmp_le_i32_e32 vcc, v121, v139
	s_nop 1
	v_cndmask_b32_e32 v63, v239, v63, vcc

; __device__ __forceinline__ unsigned cvt_pk_bf16(float lo, float hi) { const f32x2c_ v = {lo, hi}; const bf16x2c_ b = __builtin_convertvector(v, bf16x2c_); return __builtin_bit_cast(unsigned, b); }
; __device__ __forceinline__ float sum32(float v) { const auto rr = __builtin_amdgcn_permlane32_swap(__float_as_uint(v), __float_as_uint(v), false, false); return __uint_as_float(rr[0]) + __uint_as_float(rr[1]); }
; #define LAS __attribute__((address_space(3)))
; #define ATT_LOAD(t) do { kr0 = *(const u32x4*)(Kg + (size_t)(t) * 12288 + tid * 16); if (tid < 256) kr1 = *(const u32x4*)(Kg + (size_t)(t) * 12288 + (tid + 512) * 16); vr = *(const u32x4*)(Vg + (size_t)(t) * (64 * 3584)); } while (0)
; __device__ __forceinline__ void attn_unit(int bh, int qb, const bf16_t* QKV, const bf16_t* KF, const float* cstab, const float* qg, bf16_t* MIX, LAS unsigned char* lds) {
;     ...
;         LAS unsigned char* buf = lds + (t & 1) * BUFB;
;         if (t + 1 < NT) ATT_LOAD(t + 1);
; #pragma unroll
;         for (int kb = 0; kb < 2; ++kb) {
;             const int key0 = 64 * t + 32 * kb;
;             if (key0 > qw + 31) continue;
;             const LAS unsigned char* kp = buf + (32 * kb + r32) * KROW + 16 * hi;
;     ...
;         if (t + 1 < NT) { LAS unsigned char* nb = lds + ((t + 1) & 1) * BUFB; ATT_WRITE(nb); }
;         __syncthreads();
;     }
;     const float l = pg8::sum32(lrun), inv = 1.0f / l;
;     {
;         constexpr int OROW = 144;
;         LAS unsigned char* stg = lds + 2 * BUFB + wid * (32 * OROW);
; #pragma unroll
;         for (int rg = 0; rg < 4; ++rg) {
;             u32x2 w; w.x = cvt_pk_bf16(o0[4 * rg] * inv, o0[4 * rg + 1] * inv); w.y = cvt_pk_bf16(o0[4 * rg + 2] * inv, o0[4 * rg + 3] * inv);
;             u32x2 x; x.x = cvt_pk_bf16(o1[4 * rg] * inv, o1[4 * rg + 1] * inv); x.y = cvt_pk_bf16(o1[4 * rg + 2] * inv, o1[4 * rg + 3] * inv);
;             *(LAS u32x2*)(stg + r32 * OROW + (8 * rg + 4 * hi) * 2) = w; *(LAS u32x2*)(stg + r32 * OROW + (32 + 8 * rg + 4 * hi) * 2) = x;
;         }
;         asm volatile("s_waitcnt lgkmcnt(0)" ::: "memory");
;         bf16_t* dst = MIX + ((size_t)(b * SEQ + qw)) * 1024 + h * 64 + (lane & 7) * 8;
; #pragma unroll
;         for (int it = 0; it < 4; ++it) { const int row = it * 8 + (lane >> 3); const u32x4 v = *(const LAS u32x4*)(stg + row * OROW + (lane & 7) * 16); *(u32x4*)(dst + (size_t)row * 1024) = v; }
.LBB0_1118:
	s_add_i32 s19, s19, 1
	s_and_b32 s100, 1, s19
	s_cselect_b32 s100, 0, 0x6400
	v_add_u32_e32 v173, s100, v102
	v_add_u32_e32 v173, v173, v114
	v_lshl_add_u64 v[112:113], v[112:113], 0, s[82:83]
	v_lshl_add_u64 v[108:109], v[108:109], 0, s[96:97]
	s_cmp_lg_u32 s21, s14
	v_lshl_add_u64 v[110:111], v[110:111], 0, s[96:97]
	s_waitcnt lgkmcnt(0)
	s_barrier
	s_cbranch_scc1 .LBB0_1098
	v_mov_b32_e32 v32, v107
	s_nop 1
	v_permlane32_swap_b32_e32 v107, v32
	v_add_f32_e32 v32, v107, v32
	v_div_scale_f32 v33, s[4:5], v32, v32, 1.0
	v_rcp_f32_e32 v34, v33
	s_mulk_i32 s23, 0x1200
	s_add_i32 s6, s23, 0
	s_add_i32 s4, s22, s28
	v_fma_f32 v35, -v33, v34, 1.0
	v_fmac_f32_e32 v34, v35, v34
	v_div_scale_f32 v35, vcc, 1.0, v32, 1.0
	v_mul_f32_e32 v36, v35, v34
	v_fma_f32 v37, -v33, v36, v35
	v_fmac_f32_e32 v36, v37, v34
	v_fma_f32 v33, -v33, v36, v35
	v_div_fmas_f32 v33, v33, v34, v36
	v_div_fixup_f32 v32, v33, v32, 1.0
	v_mul_u32_u24_e32 v33, 0x90, v138
	v_add3_u32 v33, s6, v33, v117
	v_pk_mul_f32 v[0:1], v[0:1], v[32:33] op_sel_hi:[1,0]
	v_pk_mul_f32 v[2:3], v[2:3], v[32:33] op_sel_hi:[1,0]
	v_cvt_pk_bf16_f32 v0, v0, v1
	v_cvt_pk_bf16_f32 v1, v2, v3
	v_pk_mul_f32 v[2:3], v[16:17], v[32:33] op_sel_hi:[1,0]
	v_pk_mul_f32 v[16:17], v[18:19], v[32:33] op_sel_hi:[1,0]
	v_pk_mul_f32 v[4:5], v[4:5], v[32:33] op_sel_hi:[1,0]
	v_pk_mul_f32 v[6:7], v[6:7], v[32:33] op_sel_hi:[1,0]
	v_cvt_pk_bf16_f32 v2, v2, v3
	v_cvt_pk_bf16_f32 v3, v16, v17
	v_cvt_pk_bf16_f32 v4, v4, v5
	v_cvt_pk_bf16_f32 v5, v6, v7
	v_pk_mul_f32 v[6:7], v[20:21], v[32:33] op_sel_hi:[1,0]
	v_pk_mul_f32 v[16:17], v[22:23], v[32:33] op_sel_hi:[1,0]
	v_cvt_pk_bf16_f32 v6, v6, v7
	v_cvt_pk_bf16_f32 v7, v16, v17
	v_add_u32_e32 v16, 0xc800, v33
	ds_write2_b64 v16, v[0:1], v[4:5] offset1:2
	ds_write2_b64 v16, v[2:3], v[6:7] offset0:8 offset1:10
	v_pk_mul_f32 v[0:1], v[8:9], v[32:33] op_sel_hi:[1,0]
	v_pk_mul_f32 v[2:3], v[10:11], v[32:33] op_sel_hi:[1,0]
	v_cvt_pk_bf16_f32 v0, v0, v1
	v_cvt_pk_bf16_f32 v1, v2, v3
	v_pk_mul_f32 v[2:3], v[24:25], v[32:33] op_sel_hi:[1,0]
	v_pk_mul_f32 v[4:5], v[26:27], v[32:33] op_sel_hi:[1,0]
	v_cvt_pk_bf16_f32 v2, v2, v3
	v_cvt_pk_bf16_f32 v3, v4, v5
	v_pk_mul_f32 v[4:5], v[12:13], v[32:33] op_sel_hi:[1,0]
	v_pk_mul_f32 v[6:7], v[14:15], v[32:33] op_sel_hi:[1,0]
	v_cvt_pk_bf16_f32 v4, v4, v5
	v_cvt_pk_bf16_f32 v5, v6, v7
	v_pk_mul_f32 v[6:7], v[28:29], v[32:33] op_sel_hi:[1,0]
	v_pk_mul_f32 v[8:9], v[30:31], v[32:33] op_sel_hi:[1,0]
	s_ashr_i32 s5, s4, 31
	v_cvt_pk_bf16_f32 v6, v6, v7
	v_cvt_pk_bf16_f32 v7, v8, v9
	ds_write2_b64 v16, v[0:1], v[4:5] offset0:4 offset1:6
	ds_write2_b64 v16, v[2:3], v[6:7] offset0:12 offset1:14
	s_lshl_b64 s[4:5], s[4:5], 11
	v_lshrrev_b32_e32 v4, 3, v116
	s_add_u32 s4, s16, s4
	v_mul_u32_u24_e32 v0, 0x90, v4
	s_waitcnt lgkmcnt(0)
	s_addc_u32 s5, s17, s5
	s_lshl_b32 s2, s2, 1
	v_add3_u32 v12, s6, v64, v0
	s_add_u32 s4, s4, s2
	ds_read_b128 v[0:3], v12 offset:51200
	s_addc_u32 s5, s5, 0
	v_lshl_add_u64 v[8:9], s[4:5], 0, v[64:65]
	v_lshlrev_b32_e32 v64, 11, v4
	ds_read_b128 v[4:7], v12 offset:52352
	v_lshl_add_u64 v[10:11], v[8:9], 0, v[64:65]
	s_waitcnt lgkmcnt(1)
	global_store_dwordx4 v[10:11], v[0:3], off
	s_add_i32 s27, s27, s76
	s_add_i32 s26, s26, s76
	v_or_b32_e32 v0, 0x4000, v64
	v_mov_b32_e32 v1, v65
	v_lshl_add_u64 v[0:1], v[8:9], 0, v[0:1]
	s_waitcnt lgkmcnt(0)
	global_store_dwordx4 v[0:1], v[4:7], off
	ds_read_b128 v[0:3], v12 offset:53504
	s_cmpk_lt_i32 s27, 0x400
	v_or_b32_e32 v4, 0x8000, v64
	v_mov_b32_e32 v5, v65
	v_lshl_add_u64 v[10:11], v[8:9], 0, v[4:5]
	ds_read_b128 v[4:7], v12 offset:54656
	v_or_b32_e32 v64, 0xc000, v64
	s_waitcnt lgkmcnt(1)
	global_store_dwordx4 v[10:11], v[0:3], off
	s_nop 1
	v_lshl_add_u64 v[0:1], v[8:9], 0, v[64:65]
	s_waitcnt lgkmcnt(0)
	global_store_dwordx4 v[0:1], v[4:7], off
	s_cbranch_scc1 .LBB0_1037
